# up-projection: column tile rotated by 2*xcd (eight distinct rotations) instead of 4*(xcd&3)
# speedup vs baseline: 1.0057x; 1.0057x over previous
.LBB0_759:
	s_cmp_lt_i32 s86, 6
	s_cselect_b64 s[0:1], -1, 0
	s_and_b64 s[4:5], s[0:1], s[2:3]
	s_andn2_b64 vcc, exec, s[4:5]
	s_cbranch_vccnz .LBB0_776
	s_cmpk_gt_i32 s76, 0x17ff
	v_readfirstlane_b32 s2, v161
	s_cbranch_scc1 .LBB0_776
	v_lshrrev_b32_e32 v0, 5, v161
	v_lshrrev_b32_e32 v2, 1, v161
	v_and_b32_e32 v0, 4, v0
	s_waitcnt lgkmcnt(0)
	v_bfe_u32 v1, v161, 2, 2
	v_and_b32_e32 v11, 24, v2
	v_or3_b32 v0, v0, v1, v11
	v_lshlrev_b32_e32 v1, 4, v161
	v_add_u32_e32 v8, 0x2000, v1
	v_lshrrev_b32_e32 v2, 7, v8
	s_movk_i32 s1, 0xe0
	v_and_b32_e32 v4, 32, v161
	v_and_or_b32 v3, v2, s1, v0
	v_bitop3_b32 v9, v1, v4, 48 bitop3:0x6c
	v_and_b32_e32 v10, 64, v161
	v_bfe_u32 v12, v161, 2, 4
	s_movk_i32 s1, 0xf0
	v_or_b32_e32 v1, v9, v10
	v_and_or_b32 v2, v2, s1, v12
	v_lshl_or_b32 v130, v2, 11, v1
	v_lshrrev_b32_e32 v2, 3, v161
	s_movk_i32 s1, 0x60
	v_and_or_b32 v0, v2, s1, v0
	s_movk_i32 s1, 0x70
	v_lshl_or_b32 v132, v0, 11, v1
	v_and_or_b32 v0, v2, s1, v12
	s_ashr_i32 s1, s76, 31
	s_lshr_b32 s10, s1, 29
	s_add_i32 s10, s76, s10
	s_lshr_b32 s12, s2, 6
	s_ashr_i32 s11, s10, 3
	s_and_b32 s10, s10, -8
	s_lshr_b32 s3, s2, 8
	s_lshl_b32 s0, s12, 10
	s_sub_i32 s10, s76, s10
	s_cmp_lt_i32 s10, 0
	s_movk_i32 s14, 0x301
	s_cselect_b32 s13, s14, 0x300
	s_mul_i32 s10, s10, s13
	s_add_i32 s10, s10, s11
	s_ashr_i32 s11, s10, 31
	s_lshr_b32 s11, s11, 25
	s_add_i32 s11, s10, s11
	s_ashr_i32 s13, s11, 7
	s_and_b32 s11, s11, 0xffffff80
	s_sub_i32 s10, s10, s11
	s_bfe_i32 s11, s10, 0x80000
	s_bfe_u32 s11, s11, 0x3000c
	s_add_i32 s11, s10, s11
	s_bfe_i32 s15, s11, 0x80000
	s_and_b32 s11, s11, 0xf8
	s_sub_i32 s10, s10, s11
	s_lshl_b32 s13, s13, 3
	s_sext_i32_i16 s15, s15
	s_sext_i32_i8 s10, s10
	s_add_i32 s26, s13, s10
	s_ashr_i32 s34, s15, 3
	s_and_b32 s98, s76, 7
	s_lshl1_add_u32 s34, s98, s34
	s_and_b32 s34, s34, 15
	s_ashr_i32 s16, s15, 8
	s_ashr_i32 s27, s26, 31
	s_lshl_b32 s13, s34, 19
	s_ashr_i32 s17, s16, 31
	s_lshl_b64 s[10:11], s[26:27], 19
	s_and_b32 s13, s13, 0xf80000
	s_lshl_b64 s[16:17], s[16:17], 24
	s_add_u32 s15, s60, s16
	s_addc_u32 s16, s61, s17
	s_add_u32 s30, s15, s13
	s_addc_u32 s31, s16, 0
	s_add_i32 s15, s0, 0
	s_add_i32 m0, s15, 0x10000
	v_lshl_or_b32 v128, v3, 11, v1
	global_load_lds_dwordx4 v132, s[30:31]
	s_add_i32 m0, s15, 0x12000
	s_add_u32 s16, s30, 0x40000
	global_load_lds_dwordx4 v128, s[30:31]
	s_addc_u32 s17, s31, 0
	s_add_i32 m0, s15, 0x14000
	v_lshl_or_b32 v134, v0, 11, v1
	global_load_lds_dwordx4 v132, s[16:17]
	s_add_i32 m0, s15, 0x16000
	s_add_u32 s28, s20, s10
	s_addc_u32 s29, s21, s11
	s_add_i32 s27, s15, 0x2000
	global_load_lds_dwordx4 v128, s[16:17]
	s_mov_b32 m0, s15
	s_add_u32 s10, s28, 0x40000
	global_load_lds_dwordx4 v134, s[28:29]
	s_mov_b32 m0, s27
	s_addc_u32 s11, s29, 0
	s_add_i32 s33, s15, 0x4000
	global_load_lds_dwordx4 v130, s[28:29]
	s_mov_b32 m0, s33
	s_add_i32 s35, s15, 0x6000
	global_load_lds_dwordx4 v134, s[10:11]
	s_mov_b32 m0, s35
	v_mov_b32_e32 v133, 0
	global_load_lds_dwordx4 v130, s[10:11]
	v_mov_b32_e32 v129, v133
	v_mov_b32_e32 v135, v133
	v_mov_b32_e32 v131, v133
	s_cmp_eq_u32 s3, 1
	s_mov_b32 s38, 0
	v_lshl_add_u64 v[6:7], s[30:31], 0, v[132:133]
	v_lshl_add_u64 v[4:5], s[30:31], 0, v[128:129]
	v_lshl_add_u64 v[0:1], s[28:29], 0, v[134:135]
	s_cselect_b64 s[10:11], -1, 0
	s_cmp_lg_u32 s3, 1
	v_lshl_add_u64 v[2:3], s[28:29], 0, v[130:131]
	s_cbranch_scc1 .LBB0_763
	s_barrier

.LBB0_766:
	s_add_i32 s38, s38, 1
	s_mul_i32 s2, s38, s41
	s_mul_hi_u32 s3, s38, s85
	s_add_i32 s3, s3, s2
	s_mul_i32 s2, s38, s85
	s_add_u32 s22, s2, s76
	s_addc_u32 s23, s3, s1
	v_cmp_gt_i64_e32 vcc, s[22:23], v[142:143]
	v_cmp_lt_i64_e64 s[2:3], s[22:23], v[140:141]
	s_cbranch_vccnz .LBB0_768
	s_ashr_i32 s18, s22, 31
	s_lshr_b32 s18, s18, 29
	s_add_i32 s18, s22, s18
	s_ashr_i32 s19, s18, 3
	s_and_b32 s18, s18, -8
	s_sub_i32 s18, s22, s18
	s_cmp_lt_i32 s18, 0
	s_cselect_b32 s22, s14, 0x300
	s_mul_i32 s18, s18, s22
	s_add_i32 s18, s18, s19
	s_ashr_i32 s19, s18, 31
	s_lshr_b32 s19, s19, 25
	s_add_i32 s19, s18, s19
	s_ashr_i32 s22, s19, 7
	s_lshl_b32 s22, s22, 3
	s_sub_i32 s23, 0x180, s22
	s_min_i32 s23, s23, 8
	s_abs_i32 s24, s23
	v_cvt_f32_u32_e32 v0, s24
	s_sub_i32 s36, 0, s24
	s_and_b32 s19, s19, 0xffffff80
	s_sub_i32 s18, s18, s19
	v_rcp_iflag_f32_e32 v0, v0
	s_abs_i32 s19, s18
	s_xor_b32 s25, s18, s23
	s_ashr_i32 s25, s25, 31
	v_mul_f32_e32 v0, 0x4f7ffffe, v0
	v_cvt_u32_f32_e32 v0, v0
	s_nop 0
	v_readfirstlane_b32 s37, v0
	s_mul_i32 s36, s36, s37
	s_mul_hi_u32 s36, s37, s36
	s_add_i32 s37, s37, s36
	s_mul_hi_u32 s36, s19, s37
	s_mul_i32 s37, s36, s24
	s_sub_i32 s19, s19, s37
	s_add_i32 s48, s36, 1
	s_sub_i32 s37, s19, s24
	s_cmp_ge_u32 s19, s24
	s_cselect_b32 s36, s48, s36
	s_cselect_b32 s19, s37, s19
	s_add_i32 s37, s36, 1
	s_cmp_ge_u32 s19, s24
	s_cselect_b32 s19, s37, s36
	s_xor_b32 s19, s19, s25
	s_sub_i32 s48, s19, s25
	s_mul_i32 s19, s48, s23
	s_sub_i32 s18, s18, s19
	s_add_i32 s18, s22, s18
	s_and_b32 s98, s76, 7
	s_lshl1_add_u32 s48, s98, s48
	s_and_b32 s48, s48, 15
